# gemm_tile<BMODE=1> (FNet A/C): B-tile LDS swizzle also XORs (row>>3)&3 on the transposing ds_write_b16 and the fragment reads (16-way -> 4-way bank conflicts)
# speedup vs baseline: 1.0374x; 1.0184x over previous
.LBB0_252:
	s_add_i32 s0, s6, 0xfffffe20
	s_lshr_b32 s4, s0, 1
	s_bfe_u32 s2, s0, 0x70001
	s_lshl_b32 s0, s0, 5
	s_and_b32 s0, s0, 0x7fffe000
	s_or_b32 s78, s0, s2
	s_waitcnt vmcnt(7)
	v_mov_b32_e32 v36, v208
	s_lshl_b64 s[0:1], s[78:79], 10
	v_readlane_b32 s8, v254, 1
	v_readlane_b32 s9, v254, 2
	v_lshlrev_b32_e32 v1, 7, v36
	s_add_u32 s0, s8, s0
	v_and_b32_e32 v39, 0x2f80, v1
	v_ashrrev_i32_e32 v1, 1, v36
	s_addc_u32 s1, s9, s1
	s_lshl_b32 s2, s2, 15
	v_readlane_b32 s8, v253, 36
	v_and_b32_e32 v37, 31, v36
	v_and_b32_e32 v38, 0xffffffc0, v1
	v_ashrrev_i32_e32 v72, 3, v36
	v_readlane_b32 s9, v253, 37
	s_add_u32 s2, s8, s2
	v_lshrrev_b32_e32 v0, 5, v36
	v_and_b32_e32 v5, 7, v36
	v_or_b32_e32 v1, v38, v37
	v_ashrrev_i32_e32 v73, 31, v72
	s_addc_u32 s3, s9, 0
	v_lshl_add_u32 v100, v1, 7, v214
	v_bitop3_b32 v6, v0, v5, 1 bitop3:0x6c
	v_lshlrev_b64 v[0:1], 8, v[72:73]
	v_lshlrev_b32_e32 v3, 4, v36
	v_lshl_add_u64 v[0:1], s[2:3], 0, v[0:1]
	v_and_b32_e32 v192, 0x70, v3
	v_lshl_add_u64 v[32:33], v[0:1], 0, v[192:193]
	global_load_dwordx4 v[40:43], v[32:33], off
	s_mov_b32 s5, s79
	s_lshl_b64 s[4:5], s[4:5], 16
	v_readlane_b32 s7, v254, 5
	s_add_u32 s4, s7, s4
	v_readlane_b32 s7, v254, 6
	v_ashrrev_i32_e32 v74, 4, v36
	s_addc_u32 s5, s7, s5
	s_lshl_b32 s7, s6, 7
	v_ashrrev_i32_e32 v75, 31, v74
	s_and_b32 s7, s7, 0x80
	v_lshlrev_b32_e32 v2, 3, v36
	v_lshlrev_b64 v[0:1], 9, v[74:75]
	v_add_u32_e32 v7, 0x100, v36
	v_lshl_add_u64 v[0:1], s[4:5], 0, v[0:1]
	s_lshl_b32 s78, s7, 1
	v_and_b32_e32 v73, 0x78, v2
	v_ashrrev_i32_e32 v76, 3, v7
	v_lshl_add_u64 v[0:1], v[0:1], 0, s[78:79]
	v_lshlrev_b32_e32 v2, 1, v73
	v_mov_b32_e32 v3, v193
	v_ashrrev_i32_e32 v77, 31, v76
	v_lshl_add_u64 v[12:13], v[0:1], 0, v[2:3]
	v_lshlrev_b64 v[0:1], 8, v[76:77]
	v_bfe_u32 v4, v36, 5, 1
	v_lshl_add_u64 v[0:1], s[2:3], 0, v[0:1]
	v_lshl_add_u64 v[34:35], v[0:1], 0, v[192:193]
	v_bitop3_b32 v0, v4, v5, 2 bitop3:0x36
	v_lshlrev_b32_e32 v77, 4, v0
	v_bitop3_b32 v0, v4, v5, 4 bitop3:0x36
	v_ashrrev_i32_e32 v78, 4, v7
	v_lshlrev_b32_e32 v101, 4, v0
	v_bitop3_b32 v0, v4, v5, 6 bitop3:0x36
	v_ashrrev_i32_e32 v79, 31, v78
	v_lshlrev_b32_e32 v102, 4, v0
	v_lshlrev_b64 v[0:1], 9, v[78:79]
	v_add_u32_e32 v4, 0x200, v36
	v_lshl_add_u64 v[0:1], s[4:5], 0, v[0:1]
	v_ashrrev_i32_e32 v80, 3, v4
	v_lshl_add_u64 v[0:1], v[0:1], 0, s[78:79]
	v_ashrrev_i32_e32 v81, 31, v80
	v_lshl_add_u64 v[14:15], v[0:1], 0, v[2:3]
	v_lshlrev_b64 v[0:1], 8, v[80:81]
	v_ashrrev_i32_e32 v84, 4, v4
	v_lshl_add_u64 v[0:1], s[2:3], 0, v[0:1]
	v_ashrrev_i32_e32 v85, 31, v84
	v_lshl_add_u64 v[82:83], v[0:1], 0, v[192:193]
	v_lshlrev_b64 v[0:1], 9, v[84:85]
	v_add_u32_e32 v8, 0x300, v36
	v_lshl_add_u64 v[0:1], s[4:5], 0, v[0:1]
	v_ashrrev_i32_e32 v86, 3, v8
	v_lshl_add_u64 v[0:1], v[0:1], 0, s[78:79]
	v_ashrrev_i32_e32 v87, 31, v86
	v_lshl_add_u64 v[24:25], v[0:1], 0, v[2:3]
	v_lshlrev_b64 v[0:1], 8, v[86:87]
	v_ashrrev_i32_e32 v90, 4, v8
	v_lshl_add_u64 v[0:1], s[2:3], 0, v[0:1]
	v_ashrrev_i32_e32 v91, 31, v90
	v_lshl_add_u64 v[88:89], v[0:1], 0, v[192:193]
	v_lshlrev_b64 v[0:1], 9, v[90:91]
	v_lshl_add_u64 v[0:1], s[4:5], 0, v[0:1]
	v_lshl_add_u64 v[0:1], v[0:1], 0, s[78:79]
	v_lshl_add_u64 v[26:27], v[0:1], 0, v[2:3]
	v_xor_b32_e32 v0, v72, v36
	v_lshlrev_b32_e32 v0, 4, v0
	v_and_b32_e32 v0, 0x70, v0
	global_load_dwordx4 v[44:47], v[34:35], off
	global_load_dwordx4 v[48:51], v[12:13], off
	v_lshlrev_b32_e32 v75, 4, v6
	global_load_dwordx4 v[4:7], v[34:35], off offset:128
	global_load_dwordx4 v[52:55], v[14:15], off
	global_load_dwordx4 v[16:19], v[32:33], off offset:128
	global_load_dwordx4 v[56:59], v[82:83], off
	global_load_dwordx4 v[8:11], v[82:83], off offset:128
	v_lshl_or_b32 v134, v72, 7, v0
	global_load_dwordx4 v[60:63], v[88:89], off
	global_load_dwordx4 v[64:67], v[24:25], off
	global_load_dwordx4 v[0:3], v[88:89], off offset:128
	global_load_dwordx4 v[68:71], v[26:27], off
	s_mov_b32 s2, 0x8000
	v_add_co_u32_e32 v92, vcc, s2, v12
	s_movk_i32 s3, 0x50
	s_nop 0
	v_addc_co_u32_e32 v93, vcc, 0, v13, vcc
	v_add_co_u32_e32 v94, vcc, s2, v14
	s_movk_i32 s4, 0x60
	s_nop 0
	v_addc_co_u32_e32 v95, vcc, 0, v15, vcc
	v_add_co_u32_e32 v96, vcc, s2, v24
	global_load_dwordx4 v[28:31], v[92:93], off
	global_load_dwordx4 v[20:23], v[94:95], off
	v_addc_co_u32_e32 v97, vcc, 0, v25, vcc
	v_add_co_u32_e32 v98, vcc, s2, v26
	s_movk_i32 s2, 0x70
	s_nop 0
	v_addc_co_u32_e32 v99, vcc, 0, v27, vcc
	global_load_dwordx4 v[24:27], v[96:97], off
	global_load_dwordx4 v[12:15], v[98:99], off
	s_waitcnt vmcnt(15)
	ds_write_b128 v134, v[40:43]
	v_lshlrev_b32_e32 v40, 1, v74
	v_lshlrev_b32_e32 v41, 7, v73
	v_and_b32_e32 v42, -16, v72
	v_and_b32_e32 v40, 14, v40
	v_add_u32_e32 v43, v41, v42
	v_or_b32_e32 v135, v43, v40
	v_xad_u32 v43, v42, 16, v41
	v_or_b32_e32 v136, v43, v40
	v_xad_u32 v43, v42, 32, v41
	v_or_b32_e32 v137, v43, v40
	v_xad_u32 v43, v42, 48, v41
	v_or_b32_e32 v138, v43, v40
	v_xad_u32 v43, v42, 64, v41
	v_or_b32_e32 v139, v43, v40
	v_xad_u32 v43, v42, s3, v41
	v_or_b32_e32 v140, v43, v40
	v_xad_u32 v43, v42, s4, v41
	v_xad_u32 v42, v42, s2, v41
	v_or_b32_e32 v141, v43, v40
	v_or_b32_e32 v142, v42, v40
	v_xor_b32_e32 v40, v76, v36
	v_lshlrev_b32_e32 v40, 4, v40
	v_and_b32_e32 v40, 0x70, v40
	v_lshl_or_b32 v146, v76, 7, v40
	v_lshlrev_b32_e32 v40, 1, v78
	v_and_b32_e32 v42, -16, v76
	v_and_b32_e32 v40, 14, v40
	v_add_u32_e32 v43, v41, v42
	v_or_b32_e32 v147, v43, v40
	v_xad_u32 v43, v42, 16, v41
	v_or_b32_e32 v148, v43, v40
	v_xad_u32 v43, v42, 32, v41
	v_or_b32_e32 v149, v43, v40
	v_xad_u32 v43, v42, 48, v41
	v_or_b32_e32 v150, v43, v40
	v_xad_u32 v43, v42, 64, v41
	v_or_b32_e32 v151, v43, v40
	v_xad_u32 v43, v42, s3, v41
	v_or_b32_e32 v152, v43, v40
	v_xad_u32 v43, v42, s4, v41
	v_xad_u32 v42, v42, s2, v41
	v_or_b32_e32 v153, v43, v40
	v_or_b32_e32 v154, v42, v40
	v_xor_b32_e32 v40, v80, v36
	v_lshlrev_b32_e32 v40, 4, v40
	v_and_b32_e32 v40, 0x70, v40
	v_lshl_or_b32 v156, v80, 7, v40
	v_lshlrev_b32_e32 v40, 1, v84
	v_and_b32_e32 v42, -16, v80
	v_and_b32_e32 v40, 14, v40
	v_add_u32_e32 v43, v41, v42
	v_or_b32_e32 v157, v43, v40
	v_xad_u32 v43, v42, 16, v41
	v_or_b32_e32 v158, v43, v40
	v_xad_u32 v43, v42, 32, v41
	v_or_b32_e32 v159, v43, v40
	v_xad_u32 v43, v42, 48, v41
	v_or_b32_e32 v160, v43, v40
	v_xad_u32 v43, v42, 64, v41
	v_or_b32_e32 v161, v43, v40
	v_xad_u32 v43, v42, s3, v41
	v_or_b32_e32 v162, v43, v40
	v_xad_u32 v43, v42, s4, v41
	v_xad_u32 v42, v42, s2, v41
	v_or_b32_e32 v163, v43, v40
	v_or_b32_e32 v164, v42, v40
	v_xor_b32_e32 v40, v86, v36
	v_lshlrev_b32_e32 v40, 4, v40
	v_and_b32_e32 v40, 0x70, v40
	v_lshl_or_b32 v165, v86, 7, v40
	v_lshlrev_b32_e32 v40, 1, v90
	v_and_b32_e32 v42, -16, v86
	v_and_b32_e32 v40, 14, v40
	v_add_u32_e32 v43, v41, v42
	v_or_b32_e32 v166, v43, v40
	v_xad_u32 v43, v42, 16, v41
	v_or_b32_e32 v167, v43, v40
	v_xad_u32 v43, v42, 32, v41
	v_or_b32_e32 v168, v43, v40
	v_xad_u32 v43, v42, 48, v41
	v_or_b32_e32 v169, v43, v40
	v_xad_u32 v43, v42, 64, v41
	v_or_b32_e32 v170, v43, v40
	v_xad_u32 v43, v42, s3, v41
	v_or_b32_e32 v171, v43, v40
	v_xad_u32 v43, v42, s4, v41
	v_xad_u32 v41, v42, s2, v41
	v_or_b32_e32 v172, v43, v40
	v_or_b32_e32 v173, v41, v40
	v_and_b32_e32 v175, 3, v208
	v_lshlrev_b32_e32 v175, 4, v175
	v_bfe_u32 v176, v208, 3, 2
	v_lshlrev_b32_e32 v176, 4, v176
	v_xor_b32_e32 v135, v175, v135
	v_xor_b32_e32 v136, v175, v136
	v_xor_b32_e32 v137, v175, v137
	v_xor_b32_e32 v138, v175, v138
	v_xor_b32_e32 v139, v175, v139
	v_xor_b32_e32 v140, v175, v140
	v_xor_b32_e32 v141, v175, v141
	v_xor_b32_e32 v142, v175, v142
	v_xor_b32_e32 v147, v175, v147
	v_xor_b32_e32 v148, v175, v148
	v_xor_b32_e32 v149, v175, v149
	v_xor_b32_e32 v150, v175, v150
	v_xor_b32_e32 v151, v175, v151
	v_xor_b32_e32 v152, v175, v152
	v_xor_b32_e32 v153, v175, v153
	v_xor_b32_e32 v154, v175, v154
	v_xor_b32_e32 v157, v175, v157
	v_xor_b32_e32 v158, v175, v158
	v_xor_b32_e32 v159, v175, v159
	v_xor_b32_e32 v160, v175, v160
	v_xor_b32_e32 v161, v175, v161
	v_xor_b32_e32 v162, v175, v162
	v_xor_b32_e32 v163, v175, v163
	v_xor_b32_e32 v164, v175, v164
	v_xor_b32_e32 v166, v175, v166
	v_xor_b32_e32 v167, v175, v167
	v_xor_b32_e32 v168, v175, v168
	v_xor_b32_e32 v169, v175, v169
	v_xor_b32_e32 v170, v175, v170
	v_xor_b32_e32 v171, v175, v171
	v_xor_b32_e32 v172, v175, v172
	v_xor_b32_e32 v173, v175, v173
	s_waitcnt vmcnt(13)
	ds_write_b16 v135, v48 offset:16384
	ds_write_b16_d16_hi v136, v48 offset:16512
	ds_write_b16 v137, v49 offset:16640
	ds_write_b16_d16_hi v138, v49 offset:16768
	ds_write_b16 v139, v50 offset:16896
	ds_write_b16_d16_hi v140, v50 offset:17024
	ds_write_b16 v141, v51 offset:17152
	ds_write_b16_d16_hi v142, v51 offset:17280
	ds_write_b128 v146, v[44:47]
	s_waitcnt vmcnt(11)
	ds_write_b16 v147, v52 offset:16384
	ds_write_b16_d16_hi v148, v52 offset:16512
	ds_write_b16 v149, v53 offset:16640
	ds_write_b16_d16_hi v150, v53 offset:16768
	ds_write_b16 v151, v54 offset:16896
	ds_write_b16_d16_hi v152, v54 offset:17024
	ds_write_b16 v153, v55 offset:17152
	ds_write_b16_d16_hi v154, v55 offset:17280
	s_waitcnt vmcnt(9)
	ds_write_b128 v156, v[56:59]
	s_waitcnt vmcnt(6)
	ds_write_b16 v157, v64 offset:16384
	ds_write_b16_d16_hi v158, v64 offset:16512
	ds_write_b16 v159, v65 offset:16640
	ds_write_b16_d16_hi v160, v65 offset:16768
	ds_write_b16 v161, v66 offset:16896
	ds_write_b16_d16_hi v162, v66 offset:17024
	ds_write_b16 v163, v67 offset:17152
	ds_write_b16_d16_hi v164, v67 offset:17280
	ds_write_b128 v165, v[60:63]
	s_waitcnt vmcnt(4)
	ds_write_b16 v166, v68 offset:16384
	ds_write_b16_d16_hi v167, v68 offset:16512
	ds_write_b16 v168, v69 offset:16640
	ds_write_b16_d16_hi v169, v69 offset:16768
	ds_write_b16 v170, v70 offset:16896
	ds_write_b16_d16_hi v171, v70 offset:17024
	ds_write_b16 v172, v71 offset:17152
	ds_write_b16_d16_hi v173, v71 offset:17280
	s_waitcnt lgkmcnt(0)
	s_barrier
	global_load_dwordx4 v[40:43], v[32:33], off offset:128
	s_nop 0
	global_load_dwordx4 v[32:35], v[34:35], off offset:128
	s_nop 0
	global_load_dwordx4 v[44:47], v[82:83], off offset:128
	global_load_dwordx4 v[48:51], v[88:89], off offset:128
	global_load_dwordx4 v[52:55], v[92:93], off
	global_load_dwordx4 v[56:59], v[94:95], off
	global_load_dwordx4 v[60:63], v[96:97], off
	global_load_dwordx4 v[64:67], v[98:99], off
	v_or_b32_e32 v132, v100, v75
	v_xor_b32_e32 v132, v176, v132
	v_or_b32_e32 v143, v75, v39
	v_or_b32_e32 v144, v101, v39
	v_or_b32_e32 v145, v100, v77
	v_xor_b32_e32 v145, v176, v145
	v_or_b32_e32 v155, v102, v39
	v_or_b32_e32 v39, v77, v39
	ds_read_b128 v[68:71], v143 offset:0
	ds_read_b128 v[72:75], v143 offset:0x1000
	ds_read_b128 v[76:79], v132 offset:0
	ds_read_b128 v[80:83], v132 offset:0x1000
	v_or_b32_e32 v133, v100, v101
	v_xor_b32_e32 v133, v176, v133
	v_or_b32_e32 v174, v100, v102
	v_xor_b32_e32 v174, v176, v174
	ds_read_b128 v[84:87], v39 offset:0
	ds_read_b128 v[88:91], v39 offset:0x1000
	ds_read_b128 v[92:95], v145 offset:0
	ds_read_b128 v[96:99], v145 offset:0x1000
	ds_read_b128 v[100:103], v144 offset:0
	ds_read_b128 v[104:107], v144 offset:0x1000
	ds_read_b128 v[108:111], v133 offset:0
	ds_read_b128 v[112:115], v133 offset:0x1000
	ds_read_b128 v[116:119], v155 offset:0
	ds_read_b128 v[120:123], v155 offset:0x1000
	ds_read_b128 v[124:127], v174 offset:0
	ds_read_b128 v[128:131], v174 offset:0x1000
	s_waitcnt lgkmcnt(12)
	s_nop 0
	v_mfma_f32_32x32x16_bf16 a[48:63], v[68:71], v[76:79], 0
	s_waitcnt lgkmcnt(8)
	s_waitcnt lgkmcnt(4)
	s_waitcnt lgkmcnt(0)
	ds_write_b128 v134, v[16:19] offset:32768
	s_waitcnt vmcnt(11)
	ds_write_b16 v135, v28 offset:49152
	ds_write_b16_d16_hi v136, v28 offset:49280
	ds_write_b16 v137, v29 offset:49408
	ds_write_b16_d16_hi v138, v29 offset:49536
	ds_write_b16 v139, v30 offset:49664
	ds_write_b16_d16_hi v140, v30 offset:49792
	ds_write_b16 v141, v31 offset:49920
	ds_write_b16_d16_hi v142, v31 offset:50048
	ds_write_b128 v146, v[4:7] offset:32768
	s_waitcnt vmcnt(10)
	ds_write_b16 v147, v20 offset:49152
	ds_write_b16_d16_hi v148, v20 offset:49280
	ds_write_b16 v149, v21 offset:49408
	ds_write_b16_d16_hi v150, v21 offset:49536
	ds_write_b16 v151, v22 offset:49664
	ds_write_b16_d16_hi v152, v22 offset:49792
	ds_write_b16 v153, v23 offset:49920
	ds_write_b16_d16_hi v154, v23 offset:50048
	ds_write_b128 v156, v[8:11] offset:32768
	s_waitcnt vmcnt(9)
	ds_write_b16 v157, v24 offset:49152
	ds_write_b16_d16_hi v158, v24 offset:49280
	ds_write_b16 v159, v25 offset:49408
	ds_write_b16_d16_hi v160, v25 offset:49536
	ds_write_b16 v161, v26 offset:49664
	ds_write_b16_d16_hi v162, v26 offset:49792
	ds_write_b16 v163, v27 offset:49920
	ds_write_b16_d16_hi v164, v27 offset:50048
	ds_write_b128 v165, v[0:3] offset:32768
	s_waitcnt vmcnt(8)
	ds_write_b16 v166, v12 offset:49152
	ds_write_b16_d16_hi v167, v12 offset:49280
	ds_write_b16 v168, v13 offset:49408
	ds_write_b16_d16_hi v169, v13 offset:49536
	ds_write_b16 v170, v14 offset:49664
	ds_write_b16_d16_hi v171, v14 offset:49792
	ds_write_b16 v172, v15 offset:49920
	ds_write_b16_d16_hi v173, v15 offset:50048
	s_waitcnt lgkmcnt(0)
	s_barrier
	v_mfma_f32_32x32x16_bf16 a[48:63], v[84:87], v[92:95], a[48:63]
	ds_read_b128 v[0:3], v143 offset:0x8000
	ds_read_b128 v[4:7], v143 offset:0x9000
	ds_read_b128 v[8:11], v132 offset:0x8000
	ds_read_b128 v[12:15], v132 offset:0x9000
	ds_read_b128 v[16:19], v39 offset:0x8000
	ds_read_b128 v[20:23], v39 offset:0x9000
	ds_read_b128 v[24:27], v145 offset:0x8000
	v_mfma_f32_32x32x16_bf16 a[48:63], v[100:103], v[108:111], a[48:63]
	ds_read_b128 v[28:31], v145 offset:0x9000
	v_mfma_f32_32x32x16_bf16 a[32:47], v[68:71], v[80:83], 0
	ds_read_b128 v[68:71], v144 offset:0x8000
	v_mfma_f32_32x32x16_bf16 a[16:31], v[72:75], v[76:79], 0
	v_mfma_f32_32x32x16_bf16 a[0:15], v[72:75], v[80:83], 0
	ds_read_b128 v[72:75], v144 offset:0x9000
	ds_read_b128 v[76:79], v133 offset:0x8000
	ds_read_b128 v[80:83], v133 offset:0x9000
	v_mfma_f32_32x32x16_bf16 a[48:63], v[116:119], v[124:127], a[48:63]
	v_mfma_f32_32x32x16_bf16 a[32:47], v[84:87], v[96:99], a[32:47]
	ds_read_b128 v[84:87], v155 offset:0x8000
	v_mfma_f32_32x32x16_bf16 a[16:31], v[88:91], v[92:95], a[16:31]
	v_mfma_f32_32x32x16_bf16 a[0:15], v[88:91], v[96:99], a[0:15]
	ds_read_b128 v[88:91], v155 offset:0x9000
	ds_read_b128 v[92:95], v174 offset:0x8000
	ds_read_b128 v[96:99], v174 offset:0x9000
	s_waitcnt lgkmcnt(12)
	s_waitcnt lgkmcnt(8)
	s_waitcnt lgkmcnt(4)
	s_nop 0
	v_mfma_f32_32x32x16_bf16 a[48:63], v[0:3], v[8:11], a[48:63]
	s_waitcnt lgkmcnt(0)
	s_waitcnt vmcnt(7)
	ds_write_b128 v134, v[40:43]
	s_waitcnt vmcnt(3)
	ds_write_b16 v135, v52 offset:16384
	ds_write_b16_d16_hi v136, v52 offset:16512
	ds_write_b16 v137, v53 offset:16640
	ds_write_b16_d16_hi v138, v53 offset:16768
	ds_write_b16 v139, v54 offset:16896
	ds_write_b16_d16_hi v140, v54 offset:17024
	ds_write_b16 v141, v55 offset:17152
	ds_write_b16_d16_hi v142, v55 offset:17280
	ds_write_b128 v146, v[32:35]
	s_waitcnt vmcnt(2)
	ds_write_b16 v147, v56 offset:16384
	ds_write_b16_d16_hi v148, v56 offset:16512
	ds_write_b16 v149, v57 offset:16640
	ds_write_b16_d16_hi v150, v57 offset:16768
	ds_write_b16 v151, v58 offset:16896
	ds_write_b16_d16_hi v152, v58 offset:17024
	ds_write_b16 v153, v59 offset:17152
	ds_write_b16_d16_hi v154, v59 offset:17280
	ds_write_b128 v156, v[44:47]
	s_waitcnt vmcnt(1)
	ds_write_b16 v157, v60 offset:16384
	ds_write_b16_d16_hi v158, v60 offset:16512
	ds_write_b16 v159, v61 offset:16640
	ds_write_b16_d16_hi v160, v61 offset:16768
	ds_write_b16 v161, v62 offset:16896
	ds_write_b16_d16_hi v162, v62 offset:17024
	ds_write_b16 v163, v63 offset:17152
	ds_write_b16_d16_hi v164, v63 offset:17280
	ds_write_b128 v165, v[48:51]
	s_waitcnt vmcnt(0)
	ds_write_b16 v166, v64 offset:16384
	ds_write_b16_d16_hi v167, v64 offset:16512
	ds_write_b16 v168, v65 offset:16640
	ds_write_b16_d16_hi v169, v65 offset:16768
	ds_write_b16 v170, v66 offset:16896
	ds_write_b16_d16_hi v171, v66 offset:17024
	ds_write_b16 v172, v67 offset:17152
	ds_write_b16_d16_hi v173, v67 offset:17280
	s_waitcnt lgkmcnt(0)
	s_barrier
	v_mfma_f32_32x32x16_bf16 a[48:63], v[16:19], v[24:27], a[48:63]
	v_mfma_f32_32x32x16_bf16 a[32:47], v[100:103], v[112:115], a[32:47]
	v_mfma_f32_32x32x16_bf16 a[48:63], v[68:71], v[76:79], a[48:63]
	v_mfma_f32_32x32x16_bf16 a[16:31], v[104:107], v[108:111], a[16:31]
	v_mfma_f32_32x32x16_bf16 a[0:15], v[104:107], v[112:115], a[0:15]
	v_mfma_f32_32x32x16_bf16 a[32:47], v[116:119], v[128:131], a[32:47]
	v_mfma_f32_32x32x16_bf16 a[48:63], v[84:87], v[92:95], a[48:63]
	v_mfma_f32_32x32x16_bf16 a[16:31], v[120:123], v[124:127], a[16:31]
	v_mfma_f32_32x32x16_bf16 a[0:15], v[120:123], v[128:131], a[0:15]
	v_mfma_f32_32x32x16_bf16 a[32:47], v[0:3], v[12:15], a[32:47]
	v_and_b32_e32 v0, 64, v36
	v_lshrrev_b32_e32 v1, 3, v36
	v_and_or_b32 v2, v1, 4, v0
	v_or_b32_e32 v0, s7, v37
	v_add_u32_e32 v0, v0, v38
	s_nop 3
	v_accvgpr_read_b32 v3, a48
	v_ashrrev_i32_e32 v1, 31, v0
	v_lshlrev_b32_e32 v192, 16, v2
	v_mul_f32_e32 v2, 0x3ab504f3, v3
	v_lshl_add_u64 v[0:1], v[0:1], 1, s[0:1]
	v_bfe_u32 v3, v2, 16, 1
	v_mfma_f32_32x32x16_bf16 a[16:31], v[4:7], v[8:11], a[16:31]
	v_add3_u32 v2, v2, v3, s80
	s_mov_b32 s0, 0x20000
	v_accvgpr_read_b32 v8, a51
	v_accvgpr_read_b32 v10, a52
	v_mul_f32_e32 v10, 0x3ab504f3, v10
	v_mov_b32_e32 v9, v193
	v_accvgpr_read_b32 v11, a53
	v_mfma_f32_32x32x16_bf16 a[0:15], v[4:7], v[12:15], a[0:15]
	v_accvgpr_read_b32 v6, a49
	v_lshl_add_u64 v[4:5], v[0:1], 0, v[192:193]
	global_store_short_d16_hi v[4:5], v2, off
	v_mul_f32_e32 v2, 0x3ab504f3, v6
	v_bfe_u32 v3, v2, 16, 1
	v_accvgpr_read_b32 v7, a50
	v_add3_u32 v2, v2, v3, s80
	global_store_short_d16_hi v[4:5], v2, off offset:512
	v_mul_f32_e32 v2, 0x3ab504f3, v7
	v_bfe_u32 v3, v2, 16, 1
	v_add_co_u32_e32 v6, vcc, s0, v4
	v_add3_u32 v2, v2, v3, s80
	s_nop 0
	v_addc_co_u32_e32 v7, vcc, 0, v5, vcc
	global_store_short_d16_hi v[6:7], v2, off
	v_mul_f32_e32 v2, 0x3ab504f3, v8
	v_bfe_u32 v3, v2, 16, 1
	v_add3_u32 v2, v2, v3, s80
	v_or_b32_e32 v8, 0x80000, v192
	v_bfe_u32 v14, v10, 16, 1
	global_store_short_d16_hi v[6:7], v2, off offset:512
	v_lshl_add_u64 v[2:3], v[0:1], 0, v[8:9]
	v_add3_u32 v10, v10, v14, s80
	global_store_short_d16_hi v[2:3], v10, off
	v_mul_f32_e32 v10, 0x3ab504f3, v11
	v_bfe_u32 v11, v10, 16, 1
	v_accvgpr_read_b32 v12, a54
	v_add3_u32 v10, v10, v11, s80
	global_store_short_d16_hi v[2:3], v10, off offset:512
	v_mul_f32_e32 v10, 0x3ab504f3, v12
	v_bfe_u32 v11, v10, 16, 1
	v_add_co_u32_e32 v2, vcc, s0, v2
	v_accvgpr_read_b32 v13, a55
	v_add3_u32 v10, v10, v11, s80
	v_addc_co_u32_e32 v3, vcc, 0, v3, vcc
	global_store_short_d16_hi v[2:3], v10, off
	v_mul_f32_e32 v10, 0x3ab504f3, v13
	v_mfma_f32_32x32x16_bf16 a[32:47], v[16:19], v[28:31], a[32:47]
	v_bfe_u32 v11, v10, 16, 1
	v_accvgpr_read_b32 v12, a56
	v_add3_u32 v10, v10, v11, s80
	v_mul_f32_e32 v12, 0x3ab504f3, v12
	global_store_short_d16_hi v[2:3], v10, off offset:512
	v_or_b32_e32 v10, 0x100000, v192
	v_mov_b32_e32 v11, v193
	v_bfe_u32 v16, v12, 16, 1
	v_accvgpr_read_b32 v13, a57
	v_lshl_add_u64 v[2:3], v[0:1], 0, v[10:11]
	v_add3_u32 v12, v12, v16, s80
	global_store_short_d16_hi v[2:3], v12, off
	v_mul_f32_e32 v12, 0x3ab504f3, v13
	v_bfe_u32 v13, v12, 16, 1
	v_accvgpr_read_b32 v14, a58
	v_add3_u32 v12, v12, v13, s80
	global_store_short_d16_hi v[2:3], v12, off offset:512
	v_mul_f32_e32 v12, 0x3ab504f3, v14
	v_mfma_f32_32x32x16_bf16 a[32:47], v[68:71], v[80:83], a[32:47]
	v_bfe_u32 v13, v12, 16, 1
	v_add_co_u32_e32 v2, vcc, s0, v2
	v_accvgpr_read_b32 v15, a59
	v_add3_u32 v12, v12, v13, s80
	v_addc_co_u32_e32 v3, vcc, 0, v3, vcc
	global_store_short_d16_hi v[2:3], v12, off
	v_mul_f32_e32 v12, 0x3ab504f3, v15
	v_bfe_u32 v13, v12, 16, 1
	v_accvgpr_read_b32 v14, a60
	v_add3_u32 v12, v12, v13, s80
	v_mul_f32_e32 v14, 0x3ab504f3, v14
	global_store_short_d16_hi v[2:3], v12, off offset:512
	v_or_b32_e32 v12, 0x180000, v192
	v_mov_b32_e32 v13, v193
	v_bfe_u32 v18, v14, 16, 1
	v_accvgpr_read_b32 v15, a61
	v_lshl_add_u64 v[2:3], v[0:1], 0, v[12:13]
	v_add3_u32 v14, v14, v18, s80
	global_store_short_d16_hi v[2:3], v14, off
	v_mul_f32_e32 v14, 0x3ab504f3, v15
	v_mfma_f32_32x32x16_bf16 a[32:47], v[84:87], v[96:99], a[32:47]
	v_bfe_u32 v15, v14, 16, 1
	v_accvgpr_read_b32 v16, a62
	v_add3_u32 v14, v14, v15, s80
	global_store_short_d16_hi v[2:3], v14, off offset:512
	v_mul_f32_e32 v14, 0x3ab504f3, v16
	v_bfe_u32 v15, v14, 16, 1
	v_add_co_u32_e32 v2, vcc, s0, v2
	v_accvgpr_read_b32 v17, a63
	v_add3_u32 v14, v14, v15, s80
	v_addc_co_u32_e32 v3, vcc, 0, v3, vcc
	global_store_short_d16_hi v[2:3], v14, off
	v_mul_f32_e32 v14, 0x3ab504f3, v17
	v_bfe_u32 v15, v14, 16, 1
	v_add3_u32 v14, v14, v15, s80
	global_store_short_d16_hi v[2:3], v14, off offset:512
	v_accvgpr_read_b32 v14, a32
	v_mul_f32_e32 v14, 0x3ab504f3, v14
	v_bfe_u32 v18, v14, 16, 1
	v_accvgpr_read_b32 v15, a33
	v_add3_u32 v14, v14, v18, s80
	global_store_short_d16_hi v[4:5], v14, off offset:64
	v_mul_f32_e32 v14, 0x3ab504f3, v15
	v_bfe_u32 v15, v14, 16, 1
	v_accvgpr_read_b32 v16, a34
	v_add3_u32 v14, v14, v15, s80
	global_store_short_d16_hi v[4:5], v14, off offset:576
	v_mul_f32_e32 v4, 0x3ab504f3, v16
	v_bfe_u32 v5, v4, 16, 1
	v_accvgpr_read_b32 v17, a35
	v_add3_u32 v4, v4, v5, s80
	global_store_short_d16_hi v[6:7], v4, off offset:64
	v_mul_f32_e32 v4, 0x3ab504f3, v17
	v_bfe_u32 v5, v4, 16, 1
	v_add3_u32 v4, v4, v5, s80
	global_store_short_d16_hi v[6:7], v4, off offset:576
	v_accvgpr_read_b32 v6, a36
	v_lshl_add_u64 v[2:3], v[0:1], 0, 64
	v_mul_f32_e32 v6, 0x3ab504f3, v6
	v_lshl_add_u64 v[4:5], v[2:3], 0, v[8:9]
	v_bfe_u32 v8, v6, 16, 1
	v_accvgpr_read_b32 v7, a37
	v_add3_u32 v6, v6, v8, s80
	global_store_short_d16_hi v[4:5], v6, off
	v_mul_f32_e32 v6, 0x3ab504f3, v7
	v_bfe_u32 v7, v6, 16, 1
	v_accvgpr_read_b32 v14, a38
	v_add3_u32 v6, v6, v7, s80
	global_store_short_d16_hi v[4:5], v6, off offset:512
	v_mul_f32_e32 v6, 0x3ab504f3, v14
	v_bfe_u32 v7, v6, 16, 1
	v_add_co_u32_e32 v4, vcc, s0, v4
	v_accvgpr_read_b32 v15, a39
	v_add3_u32 v6, v6, v7, s80
	v_addc_co_u32_e32 v5, vcc, 0, v5, vcc
	global_store_short_d16_hi v[4:5], v6, off
	v_mul_f32_e32 v6, 0x3ab504f3, v15
	v_bfe_u32 v7, v6, 16, 1
	v_add3_u32 v6, v6, v7, s80
	v_mfma_f32_32x32x16_bf16 a[16:31], v[20:23], v[24:27], a[16:31]
	global_store_short_d16_hi v[4:5], v6, off offset:512
	v_accvgpr_read_b32 v6, a40
	v_mul_f32_e32 v6, 0x3ab504f3, v6
	v_lshl_add_u64 v[4:5], v[2:3], 0, v[10:11]
	v_bfe_u32 v10, v6, 16, 1
	v_accvgpr_read_b32 v7, a41
	v_add3_u32 v6, v6, v10, s80
	global_store_short_d16_hi v[4:5], v6, off
	v_mul_f32_e32 v6, 0x3ab504f3, v7
	v_bfe_u32 v7, v6, 16, 1
	v_accvgpr_read_b32 v8, a42
	v_add3_u32 v6, v6, v7, s80
	global_store_short_d16_hi v[4:5], v6, off offset:512
	v_mul_f32_e32 v6, 0x3ab504f3, v8
	v_mfma_f32_32x32x16_bf16 a[16:31], v[72:75], v[76:79], a[16:31]
	v_bfe_u32 v7, v6, 16, 1
	v_add_co_u32_e32 v4, vcc, s0, v4
	v_accvgpr_read_b32 v9, a43
	v_add3_u32 v6, v6, v7, s80
	v_addc_co_u32_e32 v5, vcc, 0, v5, vcc
	global_store_short_d16_hi v[4:5], v6, off
	v_mul_f32_e32 v6, 0x3ab504f3, v9
	v_bfe_u32 v7, v6, 16, 1
	v_add3_u32 v6, v6, v7, s80
	global_store_short_d16_hi v[4:5], v6, off offset:512
	v_accvgpr_read_b32 v6, a44
	v_mul_f32_e32 v6, 0x3ab504f3, v6
	v_bfe_u32 v10, v6, 16, 1
	v_mfma_f32_32x32x16_bf16 a[16:31], v[88:91], v[92:95], a[16:31]
	v_accvgpr_read_b32 v7, a45
	v_lshl_add_u64 v[4:5], v[2:3], 0, v[12:13]
	v_add3_u32 v6, v6, v10, s80
	global_store_short_d16_hi v[4:5], v6, off
	v_mul_f32_e32 v6, 0x3ab504f3, v7
	v_bfe_u32 v7, v6, 16, 1
	v_accvgpr_read_b32 v8, a46
	v_add3_u32 v6, v6, v7, s80
	global_store_short_d16_hi v[4:5], v6, off offset:512
	v_mul_f32_e32 v6, 0x3ab504f3, v8
	v_bfe_u32 v7, v6, 16, 1
	v_add_co_u32_e32 v4, vcc, s0, v4
	v_accvgpr_read_b32 v9, a47
	v_add3_u32 v6, v6, v7, s80
	v_addc_co_u32_e32 v5, vcc, 0, v5, vcc
	global_store_short_d16_hi v[4:5], v6, off
	v_mul_f32_e32 v6, 0x3ab504f3, v9
	v_bfe_u32 v7, v6, 16, 1
	v_accvgpr_read_b32 v8, a16
	v_add3_u32 v6, v6, v7, s80
	v_mul_f32_e32 v8, 0x3ab504f3, v8
	global_store_short_d16_hi v[4:5], v6, off offset:512
	v_or_b32_e32 v4, 0x200000, v192
	v_mov_b32_e32 v5, v193
	v_bfe_u32 v12, v8, 16, 1
	v_accvgpr_read_b32 v9, a17
	v_lshl_add_u64 v[6:7], v[0:1], 0, v[4:5]
	v_add3_u32 v8, v8, v12, s80
	global_store_short_d16_hi v[6:7], v8, off
	v_mul_f32_e32 v8, 0x3ab504f3, v9
	v_bfe_u32 v9, v8, 16, 1
	v_accvgpr_read_b32 v10, a18
	v_add3_u32 v8, v8, v9, s80
	global_store_short_d16_hi v[6:7], v8, off offset:512
	v_mul_f32_e32 v8, 0x3ab504f3, v10
	v_bfe_u32 v9, v8, 16, 1
	v_add_co_u32_e32 v6, vcc, s0, v6
	v_accvgpr_read_b32 v11, a19
	v_add3_u32 v8, v8, v9, s80
	v_addc_co_u32_e32 v7, vcc, 0, v7, vcc
	global_store_short_d16_hi v[6:7], v8, off
	v_mul_f32_e32 v8, 0x3ab504f3, v11
	v_bfe_u32 v9, v8, 16, 1
	v_accvgpr_read_b32 v10, a20
	v_add3_u32 v8, v8, v9, s80
	v_mul_f32_e32 v10, 0x3ab504f3, v10
	global_store_short_d16_hi v[6:7], v8, off offset:512
	v_or_b32_e32 v6, 0x280000, v192
	v_mov_b32_e32 v7, v193
	v_bfe_u32 v14, v10, 16, 1
	v_accvgpr_read_b32 v11, a21
	v_lshl_add_u64 v[8:9], v[0:1], 0, v[6:7]
	v_add3_u32 v10, v10, v14, s80
	global_store_short_d16_hi v[8:9], v10, off
	v_mul_f32_e32 v10, 0x3ab504f3, v11
	v_bfe_u32 v11, v10, 16, 1
	v_accvgpr_read_b32 v12, a22
	v_add3_u32 v10, v10, v11, s80
	global_store_short_d16_hi v[8:9], v10, off offset:512
	v_mul_f32_e32 v10, 0x3ab504f3, v12
	v_bfe_u32 v11, v10, 16, 1
	v_add_co_u32_e32 v8, vcc, s0, v8
	v_accvgpr_read_b32 v13, a23
	v_add3_u32 v10, v10, v11, s80
	v_addc_co_u32_e32 v9, vcc, 0, v9, vcc
	global_store_short_d16_hi v[8:9], v10, off
	v_mul_f32_e32 v10, 0x3ab504f3, v13
	v_bfe_u32 v11, v10, 16, 1
	v_accvgpr_read_b32 v12, a24
	v_add3_u32 v10, v10, v11, s80
	v_mul_f32_e32 v12, 0x3ab504f3, v12
	v_mfma_f32_32x32x16_bf16 a[0:15], v[20:23], v[28:31], a[0:15]
	global_store_short_d16_hi v[8:9], v10, off offset:512
	v_or_b32_e32 v8, 0x300000, v192
	v_mov_b32_e32 v9, v193
	v_bfe_u32 v16, v12, 16, 1
	v_accvgpr_read_b32 v13, a25
	v_lshl_add_u64 v[10:11], v[0:1], 0, v[8:9]
	v_add3_u32 v12, v12, v16, s80
	global_store_short_d16_hi v[10:11], v12, off
	v_mul_f32_e32 v12, 0x3ab504f3, v13
	v_bfe_u32 v13, v12, 16, 1
	v_accvgpr_read_b32 v14, a26
	v_add3_u32 v12, v12, v13, s80
	global_store_short_d16_hi v[10:11], v12, off offset:512
	v_mul_f32_e32 v12, 0x3ab504f3, v14
	v_bfe_u32 v13, v12, 16, 1
	v_add_co_u32_e32 v10, vcc, s0, v10
	v_accvgpr_read_b32 v15, a27
	v_add3_u32 v12, v12, v13, s80
	v_addc_co_u32_e32 v11, vcc, 0, v11, vcc
	v_mfma_f32_32x32x16_bf16 a[0:15], v[72:75], v[80:83], a[0:15]
	global_store_short_d16_hi v[10:11], v12, off
	v_mul_f32_e32 v12, 0x3ab504f3, v15
	v_bfe_u32 v13, v12, 16, 1
	v_add3_u32 v12, v12, v13, s80
	global_store_short_d16_hi v[10:11], v12, off offset:512
	v_accvgpr_read_b32 v10, a28
	v_mul_f32_e32 v10, 0x3ab504f3, v10
	v_or_b32_e32 v192, 0x380000, v192
	v_bfe_u32 v14, v10, 16, 1
	v_accvgpr_read_b32 v11, a29
	v_lshl_add_u64 v[0:1], v[0:1], 0, v[192:193]
	v_add3_u32 v10, v10, v14, s80
	global_store_short_d16_hi v[0:1], v10, off
	v_mul_f32_e32 v10, 0x3ab504f3, v11
	v_mfma_f32_32x32x16_bf16 a[0:15], v[88:91], v[96:99], a[0:15]
	v_bfe_u32 v11, v10, 16, 1
	v_accvgpr_read_b32 v12, a30
	v_add3_u32 v10, v10, v11, s80
	global_store_short_d16_hi v[0:1], v10, off offset:512
	v_mul_f32_e32 v10, 0x3ab504f3, v12
	v_bfe_u32 v11, v10, 16, 1
	v_add_co_u32_e32 v0, vcc, s0, v0
	v_accvgpr_read_b32 v13, a31
	v_add3_u32 v10, v10, v11, s80
	v_addc_co_u32_e32 v1, vcc, 0, v1, vcc
	global_store_short_d16_hi v[0:1], v10, off
	v_mul_f32_e32 v10, 0x3ab504f3, v13
	v_bfe_u32 v11, v10, 16, 1
	v_add3_u32 v10, v10, v11, s80
	global_store_short_d16_hi v[0:1], v10, off offset:512
	v_accvgpr_read_b32 v10, a0
	v_lshl_add_u64 v[0:1], v[2:3], 0, v[4:5]
	v_mul_f32_e32 v4, 0x3ab504f3, v10
	v_bfe_u32 v5, v4, 16, 1
	v_accvgpr_read_b32 v11, a1
	v_add3_u32 v4, v4, v5, s80
	global_store_short_d16_hi v[0:1], v4, off
	v_mul_f32_e32 v4, 0x3ab504f3, v11
	v_bfe_u32 v5, v4, 16, 1
	v_accvgpr_read_b32 v12, a2
	v_add3_u32 v4, v4, v5, s80
	global_store_short_d16_hi v[0:1], v4, off offset:512
	v_mul_f32_e32 v4, 0x3ab504f3, v12
	v_bfe_u32 v5, v4, 16, 1
	v_add_co_u32_e32 v0, vcc, s0, v0
	v_accvgpr_read_b32 v13, a3
	v_add3_u32 v4, v4, v5, s80
	v_addc_co_u32_e32 v1, vcc, 0, v1, vcc
	global_store_short_d16_hi v[0:1], v4, off
	v_mul_f32_e32 v4, 0x3ab504f3, v13
	v_bfe_u32 v5, v4, 16, 1
	v_add3_u32 v4, v4, v5, s80
	global_store_short_d16_hi v[0:1], v4, off offset:512
	v_accvgpr_read_b32 v4, a4
	v_mul_f32_e32 v4, 0x3ab504f3, v4
	v_lshl_add_u64 v[0:1], v[2:3], 0, v[6:7]
	v_bfe_u32 v6, v4, 16, 1
	v_accvgpr_read_b32 v5, a5
	v_add3_u32 v4, v4, v6, s80
	global_store_short_d16_hi v[0:1], v4, off
	v_mul_f32_e32 v4, 0x3ab504f3, v5
	v_bfe_u32 v5, v4, 16, 1
	v_accvgpr_read_b32 v10, a6
	v_add3_u32 v4, v4, v5, s80
	global_store_short_d16_hi v[0:1], v4, off offset:512
	v_mul_f32_e32 v4, 0x3ab504f3, v10
	v_bfe_u32 v5, v4, 16, 1
	v_add_co_u32_e32 v0, vcc, s0, v0
	v_accvgpr_read_b32 v11, a7
	v_add3_u32 v4, v4, v5, s80
	v_addc_co_u32_e32 v1, vcc, 0, v1, vcc
	global_store_short_d16_hi v[0:1], v4, off
	v_mul_f32_e32 v4, 0x3ab504f3, v11
	v_bfe_u32 v5, v4, 16, 1
	v_add3_u32 v4, v4, v5, s80
	global_store_short_d16_hi v[0:1], v4, off offset:512
	v_accvgpr_read_b32 v4, a8
	v_mul_f32_e32 v4, 0x3ab504f3, v4
	v_lshl_add_u64 v[0:1], v[2:3], 0, v[8:9]
	v_bfe_u32 v8, v4, 16, 1
	v_accvgpr_read_b32 v5, a9
	v_add3_u32 v4, v4, v8, s80
	global_store_short_d16_hi v[0:1], v4, off
	v_mul_f32_e32 v4, 0x3ab504f3, v5
	v_bfe_u32 v5, v4, 16, 1
	v_accvgpr_read_b32 v6, a10
	v_add3_u32 v4, v4, v5, s80
	global_store_short_d16_hi v[0:1], v4, off offset:512
	v_mul_f32_e32 v4, 0x3ab504f3, v6
	v_bfe_u32 v5, v4, 16, 1
	v_add_co_u32_e32 v0, vcc, s0, v0
	v_accvgpr_read_b32 v7, a11
	v_add3_u32 v4, v4, v5, s80
	v_addc_co_u32_e32 v1, vcc, 0, v1, vcc
	global_store_short_d16_hi v[0:1], v4, off
	v_mul_f32_e32 v4, 0x3ab504f3, v7
	v_bfe_u32 v5, v4, 16, 1
	v_add3_u32 v4, v4, v5, s80
	global_store_short_d16_hi v[0:1], v4, off offset:512
	v_accvgpr_read_b32 v4, a12
	v_lshl_add_u64 v[0:1], v[2:3], 0, v[192:193]
	v_mul_f32_e32 v2, 0x3ab504f3, v4
	v_bfe_u32 v3, v2, 16, 1
	v_accvgpr_read_b32 v5, a13
	v_add3_u32 v2, v2, v3, s80
	global_store_short_d16_hi v[0:1], v2, off
	v_mul_f32_e32 v2, 0x3ab504f3, v5
	v_bfe_u32 v3, v2, 16, 1
	v_accvgpr_read_b32 v6, a14
	v_add3_u32 v2, v2, v3, s80
	global_store_short_d16_hi v[0:1], v2, off offset:512
	v_mul_f32_e32 v2, 0x3ab504f3, v6
	v_bfe_u32 v3, v2, 16, 1
	v_add_co_u32_e32 v0, vcc, 0x20000, v0
	v_accvgpr_read_b32 v7, a15
	v_add3_u32 v2, v2, v3, s80
	v_addc_co_u32_e32 v1, vcc, 0, v1, vcc
	global_store_short_d16_hi v[0:1], v2, off
	v_mul_f32_e32 v2, 0x3ab504f3, v7
	v_bfe_u32 v3, v2, 16, 1
	v_add3_u32 v2, v2, v3, s80
	global_store_short_d16_hi v[0:1], v2, off offset:512
	s_cbranch_execnz .LBB0_249

.LBB0_374:
	s_andn2_b64 vcc, exec, s[0:1]
	s_cbranch_vccnz .LBB0_376
	s_add_i32 s5, s97, 0xfffffbe0
	s_lshr_b32 s78, s5, 8
	s_lshl_b64 s[0:1], s[78:79], 23
	v_readlane_b32 s2, v254, 5
	s_add_u32 s0, s2, s0
	v_readlane_b32 s2, v254, 6
	s_addc_u32 s1, s2, s1
	s_lshl_b64 s[2:3], s[78:79], 22
	v_readlane_b32 s4, v254, 11
	s_waitcnt vmcnt(7)
	v_mov_b32_e32 v37, v208
	s_add_u32 s2, s4, s2
	v_readlane_b32 s4, v254, 12
	s_addc_u32 s3, s4, s3
	v_lshlrev_b32_e32 v1, 7, v37
	s_lshl_b32 s4, s97, 7
	v_lshrrev_b32_e32 v0, 5, v37
	v_and_b32_e32 v5, 7, v37
	v_and_b32_e32 v39, 0x2f80, v1
	v_ashrrev_i32_e32 v1, 1, v37
	s_and_b32 s4, s4, 0x80
	v_and_b32_e32 v36, 31, v37
	v_and_b32_e32 v38, 0xffffffc0, v1
	v_bitop3_b32 v0, v0, v5, 1 bitop3:0x6c
	v_ashrrev_i32_e32 v110, 3, v37
	v_or_b32_e32 v1, v38, v36
	v_lshlrev_b32_e32 v109, 4, v0
	v_add_u32_e32 v0, s4, v110
	v_lshl_add_u32 v108, v1, 7, v214
	v_ashrrev_i32_e32 v1, 31, v0
	v_readlane_b32 s6, v253, 40
	v_lshlrev_b64 v[0:1], 8, v[0:1]
	v_readlane_b32 s7, v253, 41
	v_lshlrev_b32_e32 v3, 4, v37
	v_and_b32_e32 v192, 0x70, v3
	v_lshl_add_u64 v[0:1], s[6:7], 0, v[0:1]
	v_lshl_add_u64 v[32:33], v[0:1], 0, v[192:193]
	global_load_dwordx4 v[40:43], v[32:33], off
	v_ashrrev_i32_e32 v86, 4, v37
	s_lshl_b32 s5, s5, 6
	v_ashrrev_i32_e32 v87, 31, v86
	s_and_b32 s5, s5, 0x3f80
	v_lshlrev_b32_e32 v2, 3, v37
	v_lshlrev_b64 v[0:1], 15, v[86:87]
	v_lshl_add_u64 v[0:1], s[2:3], 0, v[0:1]
	s_lshl_b32 s78, s5, 1
	v_and_b32_e32 v87, 0x78, v2
	v_add_u32_e32 v7, 0x100, v37
	v_lshl_add_u64 v[0:1], v[0:1], 0, s[78:79]
	v_lshlrev_b32_e32 v2, 1, v87
	v_mov_b32_e32 v3, v193
	v_ashrrev_i32_e32 v111, 3, v7
	v_lshl_add_u64 v[12:13], v[0:1], 0, v[2:3]
	v_add_u32_e32 v0, s4, v111
	v_ashrrev_i32_e32 v1, 31, v0
	v_lshlrev_b64 v[0:1], 8, v[0:1]
	v_bfe_u32 v4, v37, 5, 1
	v_lshl_add_u64 v[0:1], s[6:7], 0, v[0:1]
	v_lshl_add_u64 v[34:35], v[0:1], 0, v[192:193]
	v_bitop3_b32 v0, v4, v5, 4 bitop3:0x36
	v_ashrrev_i32_e32 v88, 4, v7
	v_lshlrev_b32_e32 v113, 4, v0
	v_bitop3_b32 v0, v4, v5, 6 bitop3:0x36
	v_ashrrev_i32_e32 v89, 31, v88
	v_lshlrev_b32_e32 v114, 4, v0
	v_lshlrev_b64 v[0:1], 15, v[88:89]
	v_bitop3_b32 v6, v4, v5, 2 bitop3:0x36
	v_lshl_add_u64 v[0:1], s[2:3], 0, v[0:1]
	v_add_u32_e32 v4, 0x200, v37
	v_lshl_add_u64 v[0:1], v[0:1], 0, s[78:79]
	v_ashrrev_i32_e32 v89, 3, v4
	v_lshl_add_u64 v[14:15], v[0:1], 0, v[2:3]
	v_add_u32_e32 v0, s4, v89
	v_ashrrev_i32_e32 v1, 31, v0
	v_lshlrev_b64 v[0:1], 8, v[0:1]
	v_ashrrev_i32_e32 v94, 4, v4
	v_lshl_add_u64 v[0:1], s[6:7], 0, v[0:1]
	v_ashrrev_i32_e32 v95, 31, v94
	v_lshl_add_u64 v[90:91], v[0:1], 0, v[192:193]
	v_lshlrev_b64 v[0:1], 15, v[94:95]
	v_lshl_add_u64 v[0:1], s[2:3], 0, v[0:1]
	v_add_u32_e32 v8, 0x300, v37
	v_lshl_add_u64 v[0:1], v[0:1], 0, s[78:79]
	v_ashrrev_i32_e32 v95, 3, v8
	v_lshl_add_u64 v[24:25], v[0:1], 0, v[2:3]
	v_add_u32_e32 v0, s4, v95
	v_ashrrev_i32_e32 v1, 31, v0
	v_lshlrev_b64 v[0:1], 8, v[0:1]
	v_ashrrev_i32_e32 v98, 4, v8
	v_lshl_add_u64 v[0:1], s[6:7], 0, v[0:1]
	v_ashrrev_i32_e32 v99, 31, v98
	v_lshl_add_u64 v[96:97], v[0:1], 0, v[192:193]
	v_lshlrev_b64 v[0:1], 15, v[98:99]
	v_lshl_add_u64 v[0:1], s[2:3], 0, v[0:1]
	v_lshl_add_u64 v[0:1], v[0:1], 0, s[78:79]
	v_lshl_add_u64 v[26:27], v[0:1], 0, v[2:3]
	v_xor_b32_e32 v0, v110, v37
	v_lshlrev_b32_e32 v0, 4, v0
	v_and_b32_e32 v0, 0x70, v0
	global_load_dwordx4 v[44:47], v[34:35], off
	global_load_dwordx4 v[48:51], v[12:13], off
	v_lshlrev_b32_e32 v112, 4, v6
	global_load_dwordx4 v[4:7], v[34:35], off offset:128
	global_load_dwordx4 v[52:55], v[14:15], off
	global_load_dwordx4 v[16:19], v[32:33], off offset:128
	global_load_dwordx4 v[56:59], v[90:91], off
	global_load_dwordx4 v[8:11], v[90:91], off offset:128
	s_waitcnt vmcnt(12)
	v_lshl_or_b32 v152, v110, 7, v0
	global_load_dwordx4 v[60:63], v[96:97], off
	global_load_dwordx4 v[64:67], v[24:25], off
	global_load_dwordx4 v[0:3], v[96:97], off offset:128
	global_load_dwordx4 v[82:85], v[26:27], off
	s_mov_b32 s2, 0x200000
	v_add_co_u32_e32 v100, vcc, s2, v12
	s_movk_i32 s3, 0x50
	s_nop 0
	v_addc_co_u32_e32 v101, vcc, 0, v13, vcc
	v_add_co_u32_e32 v102, vcc, s2, v14
	s_movk_i32 s6, 0x60
	s_nop 0
	v_addc_co_u32_e32 v103, vcc, 0, v15, vcc
	v_add_co_u32_e32 v104, vcc, s2, v24
	global_load_dwordx4 v[28:31], v[100:101], off
	global_load_dwordx4 v[20:23], v[102:103], off
	v_addc_co_u32_e32 v105, vcc, 0, v25, vcc
	v_add_co_u32_e32 v106, vcc, s2, v26
	s_movk_i32 s2, 0x70
	s_nop 0
	v_addc_co_u32_e32 v107, vcc, 0, v27, vcc
	global_load_dwordx4 v[24:27], v[104:105], off
	global_load_dwordx4 v[12:15], v[106:107], off
	s_waitcnt vmcnt(15)
	ds_write_b128 v152, v[40:43]
	v_lshlrev_b32_e32 v40, 1, v86
	v_lshlrev_b32_e32 v41, 7, v87
	v_and_b32_e32 v42, -16, v110
	v_and_b32_e32 v40, 14, v40
	v_add_u32_e32 v43, v41, v42
	v_or_b32_e32 v153, v43, v40
	v_xad_u32 v43, v42, 16, v41
	v_or_b32_e32 v154, v43, v40
	v_xad_u32 v43, v42, 32, v41
	v_or_b32_e32 v155, v43, v40
	v_xad_u32 v43, v42, 48, v41
	v_or_b32_e32 v156, v43, v40
	v_xad_u32 v43, v42, 64, v41
	v_or_b32_e32 v157, v43, v40
	v_xad_u32 v43, v42, s3, v41
	v_or_b32_e32 v158, v43, v40
	v_xad_u32 v43, v42, s6, v41
	v_xad_u32 v42, v42, s2, v41
	v_or_b32_e32 v159, v43, v40
	v_or_b32_e32 v160, v42, v40
	v_xor_b32_e32 v40, v111, v37
	v_lshlrev_b32_e32 v40, 4, v40
	v_and_b32_e32 v40, 0x70, v40
	v_lshl_or_b32 v164, v111, 7, v40
	v_lshlrev_b32_e32 v40, 1, v88
	v_and_b32_e32 v42, -16, v111
	v_and_b32_e32 v40, 14, v40
	v_add_u32_e32 v43, v41, v42
	v_or_b32_e32 v165, v43, v40
	v_xad_u32 v43, v42, 16, v41
	v_or_b32_e32 v166, v43, v40
	v_xad_u32 v43, v42, 32, v41
	v_or_b32_e32 v167, v43, v40
	v_xad_u32 v43, v42, 48, v41
	v_or_b32_e32 v168, v43, v40
	v_xad_u32 v43, v42, 64, v41
	v_or_b32_e32 v169, v43, v40
	v_xad_u32 v43, v42, s3, v41
	v_or_b32_e32 v170, v43, v40
	v_xad_u32 v43, v42, s6, v41
	v_xad_u32 v42, v42, s2, v41
	v_or_b32_e32 v171, v43, v40
	v_or_b32_e32 v172, v42, v40
	v_xor_b32_e32 v40, v89, v37
	v_lshlrev_b32_e32 v40, 4, v40
	v_and_b32_e32 v40, 0x70, v40
	v_lshl_or_b32 v174, v89, 7, v40
	v_lshlrev_b32_e32 v40, 1, v94
	v_and_b32_e32 v42, -16, v89
	v_and_b32_e32 v40, 14, v40
	v_add_u32_e32 v43, v41, v42
	v_or_b32_e32 v175, v43, v40
	v_xad_u32 v43, v42, 16, v41
	v_or_b32_e32 v176, v43, v40
	v_xad_u32 v43, v42, 32, v41
	v_or_b32_e32 v177, v43, v40
	v_xad_u32 v43, v42, 48, v41
	v_or_b32_e32 v178, v43, v40
	v_xad_u32 v43, v42, 64, v41
	v_or_b32_e32 v179, v43, v40
	v_xad_u32 v43, v42, s3, v41
	v_or_b32_e32 v180, v43, v40
	v_xad_u32 v43, v42, s6, v41
	v_xad_u32 v42, v42, s2, v41
	v_or_b32_e32 v181, v43, v40
	v_or_b32_e32 v182, v42, v40
	v_xor_b32_e32 v40, v95, v37
	v_lshlrev_b32_e32 v40, 4, v40
	v_and_b32_e32 v40, 0x70, v40
	v_lshl_or_b32 v183, v95, 7, v40
	v_lshlrev_b32_e32 v40, 1, v98
	v_and_b32_e32 v42, -16, v95
	v_and_b32_e32 v40, 14, v40
	v_add_u32_e32 v43, v41, v42
	v_or_b32_e32 v184, v43, v40
	v_xad_u32 v43, v42, 16, v41
	v_or_b32_e32 v185, v43, v40
	v_xad_u32 v43, v42, 32, v41
	v_or_b32_e32 v186, v43, v40
	v_xad_u32 v43, v42, 48, v41
	v_or_b32_e32 v187, v43, v40
	v_xad_u32 v43, v42, 64, v41
	v_or_b32_e32 v188, v43, v40
	v_xad_u32 v43, v42, s3, v41
	v_or_b32_e32 v189, v43, v40
	v_xad_u32 v43, v42, s6, v41
	v_xad_u32 v41, v42, s2, v41
	v_or_b32_e32 v190, v43, v40
	v_or_b32_e32 v191, v41, v40
	v_and_b32_e32 v75, 3, v208
	v_lshlrev_b32_e32 v75, 4, v75
	v_bfe_u32 v92, v208, 3, 2
	v_lshlrev_b32_e32 v92, 4, v92
	v_xor_b32_e32 v153, v75, v153
	v_xor_b32_e32 v154, v75, v154
	v_xor_b32_e32 v155, v75, v155
	v_xor_b32_e32 v156, v75, v156
	v_xor_b32_e32 v157, v75, v157
	v_xor_b32_e32 v158, v75, v158
	v_xor_b32_e32 v159, v75, v159
	v_xor_b32_e32 v160, v75, v160
	v_xor_b32_e32 v165, v75, v165
	v_xor_b32_e32 v166, v75, v166
	v_xor_b32_e32 v167, v75, v167
	v_xor_b32_e32 v168, v75, v168
	v_xor_b32_e32 v169, v75, v169
	v_xor_b32_e32 v170, v75, v170
	v_xor_b32_e32 v171, v75, v171
	v_xor_b32_e32 v172, v75, v172
	v_xor_b32_e32 v175, v75, v175
	v_xor_b32_e32 v176, v75, v176
	v_xor_b32_e32 v177, v75, v177
	v_xor_b32_e32 v178, v75, v178
	v_xor_b32_e32 v179, v75, v179
	v_xor_b32_e32 v180, v75, v180
	v_xor_b32_e32 v181, v75, v181
	v_xor_b32_e32 v182, v75, v182
	v_xor_b32_e32 v184, v75, v184
	v_xor_b32_e32 v185, v75, v185
	v_xor_b32_e32 v186, v75, v186
	v_xor_b32_e32 v187, v75, v187
	v_xor_b32_e32 v188, v75, v188
	v_xor_b32_e32 v189, v75, v189
	v_xor_b32_e32 v190, v75, v190
	v_xor_b32_e32 v191, v75, v191
	s_waitcnt vmcnt(13)
	ds_write_b16 v153, v48 offset:16384
	ds_write_b16_d16_hi v154, v48 offset:16512
	ds_write_b16 v155, v49 offset:16640
	ds_write_b16_d16_hi v156, v49 offset:16768
	ds_write_b16 v157, v50 offset:16896
	ds_write_b16_d16_hi v158, v50 offset:17024
	ds_write_b16 v159, v51 offset:17152
	ds_write_b16_d16_hi v160, v51 offset:17280
	ds_write_b128 v164, v[44:47]
	s_waitcnt vmcnt(11)
	ds_write_b16 v165, v52 offset:16384
	ds_write_b16_d16_hi v166, v52 offset:16512
	ds_write_b16 v167, v53 offset:16640
	ds_write_b16_d16_hi v168, v53 offset:16768
	ds_write_b16 v169, v54 offset:16896
	ds_write_b16_d16_hi v170, v54 offset:17024
	ds_write_b16 v171, v55 offset:17152
	ds_write_b16_d16_hi v172, v55 offset:17280
	s_waitcnt vmcnt(9)
	ds_write_b128 v174, v[56:59]
	s_waitcnt vmcnt(6)
	ds_write_b16 v175, v64 offset:16384
	ds_write_b16_d16_hi v176, v64 offset:16512
	ds_write_b16 v177, v65 offset:16640
	ds_write_b16_d16_hi v178, v65 offset:16768
	ds_write_b16 v179, v66 offset:16896
	ds_write_b16_d16_hi v180, v66 offset:17024
	ds_write_b16 v181, v67 offset:17152
	ds_write_b16_d16_hi v182, v67 offset:17280
	ds_write_b128 v183, v[60:63]
	s_waitcnt vmcnt(4)
	ds_write_b16 v184, v82 offset:16384
	ds_write_b16_d16_hi v185, v82 offset:16512
	ds_write_b16 v186, v83 offset:16640
	ds_write_b16_d16_hi v187, v83 offset:16768
	ds_write_b16 v188, v84 offset:16896
	ds_write_b16_d16_hi v189, v84 offset:17024
	ds_write_b16 v190, v85 offset:17152
	ds_write_b16_d16_hi v191, v85 offset:17280
	s_waitcnt lgkmcnt(0)
	s_barrier
	global_load_dwordx4 v[40:43], v[32:33], off offset:128
	s_nop 0
	global_load_dwordx4 v[32:35], v[34:35], off offset:128
	s_nop 0
	global_load_dwordx4 v[44:47], v[90:91], off offset:128
	global_load_dwordx4 v[48:51], v[96:97], off offset:128
	global_load_dwordx4 v[52:55], v[100:101], off
	global_load_dwordx4 v[56:59], v[102:103], off
	global_load_dwordx4 v[60:63], v[104:105], off
	global_load_dwordx4 v[64:67], v[106:107], off
	v_or_b32_e32 v150, v108, v109
	v_xor_b32_e32 v150, v92, v150
	v_or_b32_e32 v161, v109, v39
	ds_read_b128 v[82:85], v161 offset:0
	ds_read_b128 v[86:89], v161 offset:0x1000
	ds_read_b128 v[94:97], v150 offset:0
	ds_read_b128 v[98:101], v150 offset:0x1000
	v_or_b32_e32 v151, v108, v113
	v_xor_b32_e32 v151, v92, v151
	v_or_b32_e32 v162, v113, v39
	v_or_b32_e32 v163, v108, v112
	v_xor_b32_e32 v163, v92, v163
	v_or_b32_e32 v173, v114, v39
	v_or_b32_e32 v39, v112, v39
	v_or_b32_e32 v192, v108, v114
	v_xor_b32_e32 v192, v92, v192
	ds_read_b128 v[102:105], v39 offset:0
	ds_read_b128 v[106:109], v39 offset:0x1000
	ds_read_b128 v[110:113], v163 offset:0
	ds_read_b128 v[114:117], v163 offset:0x1000
	ds_read_b128 v[118:121], v162 offset:0
	ds_read_b128 v[122:125], v162 offset:0x1000
	ds_read_b128 v[126:129], v151 offset:0
	ds_read_b128 v[130:133], v151 offset:0x1000
	ds_read_b128 v[134:137], v173 offset:0
	ds_read_b128 v[138:141], v173 offset:0x1000
	ds_read_b128 v[142:145], v192 offset:0
	ds_read_b128 v[146:149], v192 offset:0x1000
	s_waitcnt lgkmcnt(12)
	s_nop 0
	v_mfma_f32_32x32x16_bf16 a[48:63], v[82:85], v[94:97], 0
	s_waitcnt lgkmcnt(8)
	s_waitcnt lgkmcnt(4)
	s_waitcnt lgkmcnt(0)
	ds_write_b128 v152, v[16:19] offset:32768
	s_waitcnt vmcnt(11)
	ds_write_b16 v153, v28 offset:49152
	ds_write_b16_d16_hi v154, v28 offset:49280
	ds_write_b16 v155, v29 offset:49408
	ds_write_b16_d16_hi v156, v29 offset:49536
	ds_write_b16 v157, v30 offset:49664
	ds_write_b16_d16_hi v158, v30 offset:49792
	ds_write_b16 v159, v31 offset:49920
	ds_write_b16_d16_hi v160, v31 offset:50048
	ds_write_b128 v164, v[4:7] offset:32768
	s_waitcnt vmcnt(10)
	ds_write_b16 v165, v20 offset:49152
	ds_write_b16_d16_hi v166, v20 offset:49280
	ds_write_b16 v167, v21 offset:49408
	ds_write_b16_d16_hi v168, v21 offset:49536
	ds_write_b16 v169, v22 offset:49664
	ds_write_b16_d16_hi v170, v22 offset:49792
	ds_write_b16 v171, v23 offset:49920
	ds_write_b16_d16_hi v172, v23 offset:50048
	ds_write_b128 v174, v[8:11] offset:32768
	s_waitcnt vmcnt(9)
	ds_write_b16 v175, v24 offset:49152
	ds_write_b16_d16_hi v176, v24 offset:49280
	ds_write_b16 v177, v25 offset:49408
	ds_write_b16_d16_hi v178, v25 offset:49536
	ds_write_b16 v179, v26 offset:49664
	ds_write_b16_d16_hi v180, v26 offset:49792
	ds_write_b16 v181, v27 offset:49920
	ds_write_b16_d16_hi v182, v27 offset:50048
	ds_write_b128 v183, v[0:3] offset:32768
	s_waitcnt vmcnt(8)
	ds_write_b16 v184, v12 offset:49152
	ds_write_b16_d16_hi v185, v12 offset:49280
	ds_write_b16 v186, v13 offset:49408
	ds_write_b16_d16_hi v187, v13 offset:49536
	ds_write_b16 v188, v14 offset:49664
	ds_write_b16_d16_hi v189, v14 offset:49792
	ds_write_b16 v190, v15 offset:49920
	ds_write_b16_d16_hi v191, v15 offset:50048
	s_waitcnt lgkmcnt(0)
	s_barrier
	v_mfma_f32_32x32x16_bf16 a[48:63], v[102:105], v[110:113], a[48:63]
	ds_read_b128 v[0:3], v161 offset:0x8000
	ds_read_b128 v[4:7], v161 offset:0x9000
	ds_read_b128 v[8:11], v150 offset:0x8000
	ds_read_b128 v[12:15], v150 offset:0x9000
	ds_read_b128 v[16:19], v39 offset:0x8000
	ds_read_b128 v[20:23], v39 offset:0x9000
	ds_read_b128 v[24:27], v163 offset:0x8000
	v_mfma_f32_32x32x16_bf16 a[48:63], v[118:121], v[126:129], a[48:63]
	ds_read_b128 v[28:31], v163 offset:0x9000
	v_mfma_f32_32x32x16_bf16 a[32:47], v[82:85], v[98:101], 0
	ds_read_b128 v[82:85], v162 offset:0x8000
	v_mfma_f32_32x32x16_bf16 a[16:31], v[86:89], v[94:97], 0
	v_mfma_f32_32x32x16_bf16 a[0:15], v[86:89], v[98:101], 0
	ds_read_b128 v[86:89], v162 offset:0x9000
	ds_read_b128 v[94:97], v151 offset:0x8000
	ds_read_b128 v[98:101], v151 offset:0x9000
	v_mfma_f32_32x32x16_bf16 a[48:63], v[134:137], v[142:145], a[48:63]
	v_mfma_f32_32x32x16_bf16 a[32:47], v[102:105], v[114:117], a[32:47]
	ds_read_b128 v[102:105], v173 offset:0x8000
	v_mfma_f32_32x32x16_bf16 a[16:31], v[106:109], v[110:113], a[16:31]
	v_mfma_f32_32x32x16_bf16 a[0:15], v[106:109], v[114:117], a[0:15]
	ds_read_b128 v[106:109], v173 offset:0x9000
	ds_read_b128 v[110:113], v192 offset:0x8000
	ds_read_b128 v[114:117], v192 offset:0x9000
	s_waitcnt lgkmcnt(12)
	s_waitcnt lgkmcnt(8)
	s_waitcnt lgkmcnt(4)
	s_nop 0
	v_mfma_f32_32x32x16_bf16 a[48:63], v[0:3], v[8:11], a[48:63]
	s_waitcnt lgkmcnt(0)
	s_waitcnt vmcnt(7)
	ds_write_b128 v152, v[40:43]
	s_waitcnt vmcnt(3)
	ds_write_b16 v153, v52 offset:16384
	ds_write_b16_d16_hi v154, v52 offset:16512
	ds_write_b16 v155, v53 offset:16640
	ds_write_b16_d16_hi v156, v53 offset:16768
	ds_write_b16 v157, v54 offset:16896
	ds_write_b16_d16_hi v158, v54 offset:17024
	ds_write_b16 v159, v55 offset:17152
	ds_write_b16_d16_hi v160, v55 offset:17280
	ds_write_b128 v164, v[32:35]
	s_waitcnt vmcnt(2)
	ds_write_b16 v165, v56 offset:16384
	ds_write_b16_d16_hi v166, v56 offset:16512
	ds_write_b16 v167, v57 offset:16640
	ds_write_b16_d16_hi v168, v57 offset:16768
	ds_write_b16 v169, v58 offset:16896
	ds_write_b16_d16_hi v170, v58 offset:17024
	ds_write_b16 v171, v59 offset:17152
	ds_write_b16_d16_hi v172, v59 offset:17280
	ds_write_b128 v174, v[44:47]
	s_waitcnt vmcnt(1)
	ds_write_b16 v175, v60 offset:16384
	ds_write_b16_d16_hi v176, v60 offset:16512
	ds_write_b16 v177, v61 offset:16640
	ds_write_b16_d16_hi v178, v61 offset:16768
	ds_write_b16 v179, v62 offset:16896
	ds_write_b16_d16_hi v180, v62 offset:17024
	ds_write_b16 v181, v63 offset:17152
	ds_write_b16_d16_hi v182, v63 offset:17280
	ds_write_b128 v183, v[48:51]
	s_waitcnt vmcnt(0)
	ds_write_b16 v184, v64 offset:16384
	ds_write_b16_d16_hi v185, v64 offset:16512
	ds_write_b16 v186, v65 offset:16640
	ds_write_b16_d16_hi v187, v65 offset:16768
	ds_write_b16 v188, v66 offset:16896
	ds_write_b16_d16_hi v189, v66 offset:17024
	ds_write_b16 v190, v67 offset:17152
	ds_write_b16_d16_hi v191, v67 offset:17280
	s_waitcnt lgkmcnt(0)
	s_barrier
	v_mfma_f32_32x32x16_bf16 a[32:47], v[118:121], v[130:133], a[32:47]
	v_mfma_f32_32x32x16_bf16 a[48:63], v[16:19], v[24:27], a[48:63]
	v_mfma_f32_32x32x16_bf16 a[16:31], v[122:125], v[126:129], a[16:31]
	v_mfma_f32_32x32x16_bf16 a[0:15], v[122:125], v[130:133], a[0:15]
	v_mfma_f32_32x32x16_bf16 a[32:47], v[134:137], v[146:149], a[32:47]
	v_mfma_f32_32x32x16_bf16 a[48:63], v[82:85], v[94:97], a[48:63]
	v_mfma_f32_32x32x16_bf16 a[16:31], v[138:141], v[142:145], a[16:31]
	v_mfma_f32_32x32x16_bf16 a[0:15], v[138:141], v[146:149], a[0:15]
	v_mfma_f32_32x32x16_bf16 a[32:47], v[0:3], v[12:15], a[32:47]
	v_lshrrev_b32_e32 v1, 3, v37
	v_and_b32_e32 v0, 64, v37
	v_and_b32_e32 v1, 4, v1
	v_or3_b32 v2, v0, v1, s4
	v_or_b32_e32 v0, s5, v36
	v_add_u32_e32 v0, v0, v38
	v_and_b32_e32 v1, 0xdf, v0
	v_mfma_f32_32x32x16_bf16 a[48:63], v[102:105], v[110:113], a[48:63]
	v_ashrrev_i32_e32 v0, 7, v0
	v_and_b32_e32 v3, -2, v0
	v_lshl_add_u32 v2, v2, 6, v3
	v_ashrrev_i32_e32 v3, 31, v2
	v_lshlrev_b32_e32 v192, 1, v1
	v_lshl_add_u64 v[0:1], s[0:1], 0, v[192:193]
	s_mov_b32 s0, 0x10000
	v_mfma_f32_32x32x16_bf16 a[16:31], v[4:7], v[8:11], a[16:31]
	v_mfma_f32_32x32x16_bf16 a[0:15], v[4:7], v[12:15], a[0:15]
	v_lshlrev_b64 v[4:5], 9, v[2:3]
	s_nop 1
	v_accvgpr_read_b32 v3, a48
	v_bfe_u32 v6, v3, 16, 1
	v_lshl_add_u64 v[4:5], v[0:1], 0, v[4:5]
	v_add3_u32 v3, v3, v6, s80
	global_store_short_d16_hi v[4:5], v3, off
	v_accvgpr_read_b32 v3, a49
	v_bfe_u32 v6, v3, 16, 1
	v_add3_u32 v3, v3, v6, s80
	global_store_short_d16_hi v[4:5], v3, off offset:512
	v_accvgpr_read_b32 v3, a50
	v_bfe_u32 v6, v3, 16, 1
	v_add3_u32 v3, v3, v6, s80
	v_add_co_u32_e32 v6, vcc, s0, v4
	v_mfma_f32_32x32x16_bf16 a[32:47], v[16:19], v[28:31], a[32:47]
	s_nop 0
	v_addc_co_u32_e32 v7, vcc, 0, v5, vcc
	global_store_short_d16_hi v[6:7], v3, off
	v_accvgpr_read_b32 v3, a51
	v_bfe_u32 v8, v3, 16, 1
	v_add3_u32 v3, v3, v8, s80
	v_add_u32_e32 v8, 0x200, v2
	global_store_short_d16_hi v[6:7], v3, off offset:512
	v_ashrrev_i32_e32 v9, 31, v8
	v_accvgpr_read_b32 v3, a52
	v_lshlrev_b64 v[8:9], 9, v[8:9]
	v_bfe_u32 v10, v3, 16, 1
	v_lshl_add_u64 v[8:9], v[0:1], 0, v[8:9]
	v_add3_u32 v3, v3, v10, s80
	global_store_short_d16_hi v[8:9], v3, off
	v_accvgpr_read_b32 v3, a53
	v_bfe_u32 v10, v3, 16, 1
	v_add3_u32 v3, v3, v10, s80
	global_store_short_d16_hi v[8:9], v3, off offset:512
	v_accvgpr_read_b32 v3, a54
	v_bfe_u32 v10, v3, 16, 1
	v_add3_u32 v3, v3, v10, s80
	v_add_co_u32_e32 v10, vcc, s0, v8
	v_mfma_f32_32x32x16_bf16 a[32:47], v[82:85], v[98:101], a[32:47]
	s_nop 0
	v_addc_co_u32_e32 v11, vcc, 0, v9, vcc
	global_store_short_d16_hi v[10:11], v3, off
	v_accvgpr_read_b32 v3, a55
	v_bfe_u32 v12, v3, 16, 1
	v_add3_u32 v3, v3, v12, s80
	v_add_u32_e32 v12, 0x400, v2
	global_store_short_d16_hi v[10:11], v3, off offset:512
	v_ashrrev_i32_e32 v13, 31, v12
	v_accvgpr_read_b32 v3, a56
	v_lshlrev_b64 v[12:13], 9, v[12:13]
	v_bfe_u32 v14, v3, 16, 1
	v_lshl_add_u64 v[12:13], v[0:1], 0, v[12:13]
	v_add3_u32 v3, v3, v14, s80
	global_store_short_d16_hi v[12:13], v3, off
	v_accvgpr_read_b32 v3, a57
	v_bfe_u32 v14, v3, 16, 1
	v_add3_u32 v3, v3, v14, s80
	global_store_short_d16_hi v[12:13], v3, off offset:512
	v_accvgpr_read_b32 v3, a58
	v_bfe_u32 v14, v3, 16, 1
	v_add3_u32 v3, v3, v14, s80
	v_add_co_u32_e32 v14, vcc, s0, v12
	v_mfma_f32_32x32x16_bf16 a[32:47], v[102:105], v[114:117], a[32:47]
	s_nop 0
	v_addc_co_u32_e32 v15, vcc, 0, v13, vcc
	global_store_short_d16_hi v[14:15], v3, off
	v_accvgpr_read_b32 v3, a59
	v_bfe_u32 v16, v3, 16, 1
	v_add3_u32 v3, v3, v16, s80
	v_add_u32_e32 v16, 0x600, v2
	global_store_short_d16_hi v[14:15], v3, off offset:512
	v_ashrrev_i32_e32 v17, 31, v16
	v_accvgpr_read_b32 v3, a60
	v_lshlrev_b64 v[16:17], 9, v[16:17]
	v_bfe_u32 v18, v3, 16, 1
	v_lshl_add_u64 v[16:17], v[0:1], 0, v[16:17]
	v_add3_u32 v3, v3, v18, s80
	global_store_short_d16_hi v[16:17], v3, off
	v_accvgpr_read_b32 v3, a61
	v_bfe_u32 v18, v3, 16, 1
	v_add3_u32 v3, v3, v18, s80
	global_store_short_d16_hi v[16:17], v3, off offset:512
	v_accvgpr_read_b32 v3, a62
	v_bfe_u32 v18, v3, 16, 1
	v_add3_u32 v3, v3, v18, s80
	v_add_co_u32_e32 v18, vcc, s0, v16
	v_mfma_f32_32x32x16_bf16 a[16:31], v[20:23], v[24:27], a[16:31]
	s_nop 0
	v_addc_co_u32_e32 v19, vcc, 0, v17, vcc
	global_store_short_d16_hi v[18:19], v3, off
	v_accvgpr_read_b32 v3, a63
	v_mfma_f32_32x32x16_bf16 a[0:15], v[20:23], v[28:31], a[0:15]
	v_bfe_u32 v20, v3, 16, 1
	v_add3_u32 v3, v3, v20, s80
	global_store_short_d16_hi v[18:19], v3, off offset:512
	v_accvgpr_read_b32 v3, a32
	v_bfe_u32 v20, v3, 16, 1
	v_add3_u32 v3, v3, v20, s80
	global_store_short_d16_hi v[4:5], v3, off offset:64
	v_accvgpr_read_b32 v3, a33
	v_bfe_u32 v20, v3, 16, 1
	v_add3_u32 v3, v3, v20, s80
	global_store_short_d16_hi v[4:5], v3, off offset:576
	v_accvgpr_read_b32 v3, a34
	v_bfe_u32 v4, v3, 16, 1
	v_add3_u32 v3, v3, v4, s80
	global_store_short_d16_hi v[6:7], v3, off offset:64
	v_accvgpr_read_b32 v3, a35
	v_bfe_u32 v4, v3, 16, 1
	v_add3_u32 v3, v3, v4, s80
	global_store_short_d16_hi v[6:7], v3, off offset:576
	v_accvgpr_read_b32 v3, a36
	v_bfe_u32 v4, v3, 16, 1
	v_add3_u32 v3, v3, v4, s80
	global_store_short_d16_hi v[8:9], v3, off offset:64
	v_accvgpr_read_b32 v3, a37
	v_bfe_u32 v4, v3, 16, 1
	v_add3_u32 v3, v3, v4, s80
	global_store_short_d16_hi v[8:9], v3, off offset:576
	v_accvgpr_read_b32 v3, a38
	v_bfe_u32 v4, v3, 16, 1
	v_add3_u32 v3, v3, v4, s80
	global_store_short_d16_hi v[10:11], v3, off offset:64
	v_accvgpr_read_b32 v3, a39
	v_bfe_u32 v4, v3, 16, 1
	v_add3_u32 v3, v3, v4, s80
	global_store_short_d16_hi v[10:11], v3, off offset:576
	v_accvgpr_read_b32 v3, a40
	v_bfe_u32 v4, v3, 16, 1
	v_add3_u32 v3, v3, v4, s80
	global_store_short_d16_hi v[12:13], v3, off offset:64
	v_accvgpr_read_b32 v3, a41
	v_bfe_u32 v4, v3, 16, 1
	v_add3_u32 v3, v3, v4, s80
	global_store_short_d16_hi v[12:13], v3, off offset:576
	v_accvgpr_read_b32 v3, a42
	v_bfe_u32 v4, v3, 16, 1
	v_mfma_f32_32x32x16_bf16 a[16:31], v[86:89], v[94:97], a[16:31]
	v_add3_u32 v3, v3, v4, s80
	global_store_short_d16_hi v[14:15], v3, off offset:64
	v_accvgpr_read_b32 v3, a43
	v_bfe_u32 v4, v3, 16, 1
	v_add3_u32 v3, v3, v4, s80
	global_store_short_d16_hi v[14:15], v3, off offset:576
	v_accvgpr_read_b32 v3, a44
	v_bfe_u32 v4, v3, 16, 1
	v_add3_u32 v3, v3, v4, s80
	global_store_short_d16_hi v[16:17], v3, off offset:64
	v_accvgpr_read_b32 v3, a45
	v_mfma_f32_32x32x16_bf16 a[16:31], v[106:109], v[110:113], a[16:31]
	v_bfe_u32 v4, v3, 16, 1
	v_add3_u32 v3, v3, v4, s80
	global_store_short_d16_hi v[16:17], v3, off offset:576
	v_accvgpr_read_b32 v3, a46
	v_bfe_u32 v4, v3, 16, 1
	v_add3_u32 v3, v3, v4, s80
	global_store_short_d16_hi v[18:19], v3, off offset:64
	v_accvgpr_read_b32 v3, a47
	v_bfe_u32 v4, v3, 16, 1
	v_add3_u32 v3, v3, v4, s80
	v_add_u32_e32 v4, 0x800, v2
	global_store_short_d16_hi v[18:19], v3, off offset:576
	v_ashrrev_i32_e32 v5, 31, v4
	v_accvgpr_read_b32 v3, a16
	v_lshlrev_b64 v[4:5], 9, v[4:5]
	v_bfe_u32 v6, v3, 16, 1
	v_lshl_add_u64 v[4:5], v[0:1], 0, v[4:5]
	v_add3_u32 v3, v3, v6, s80
	global_store_short_d16_hi v[4:5], v3, off
	v_accvgpr_read_b32 v3, a17
	v_bfe_u32 v6, v3, 16, 1
	v_add3_u32 v3, v3, v6, s80
	global_store_short_d16_hi v[4:5], v3, off offset:512
	v_accvgpr_read_b32 v3, a18
	v_bfe_u32 v6, v3, 16, 1
	v_add3_u32 v3, v3, v6, s80
	v_add_co_u32_e32 v6, vcc, s0, v4
	v_mfma_f32_32x32x16_bf16 a[0:15], v[86:89], v[98:101], a[0:15]
	s_nop 0
	v_addc_co_u32_e32 v7, vcc, 0, v5, vcc
	global_store_short_d16_hi v[6:7], v3, off
	v_accvgpr_read_b32 v3, a19
	v_bfe_u32 v8, v3, 16, 1
	v_add3_u32 v3, v3, v8, s80
	v_add_u32_e32 v8, 0xa00, v2
	global_store_short_d16_hi v[6:7], v3, off offset:512
	v_ashrrev_i32_e32 v9, 31, v8
	v_accvgpr_read_b32 v3, a20
	v_lshlrev_b64 v[8:9], 9, v[8:9]
	v_bfe_u32 v10, v3, 16, 1
	v_lshl_add_u64 v[8:9], v[0:1], 0, v[8:9]
	v_add3_u32 v3, v3, v10, s80
	global_store_short_d16_hi v[8:9], v3, off
	v_accvgpr_read_b32 v3, a21
	v_bfe_u32 v10, v3, 16, 1
	v_add3_u32 v3, v3, v10, s80
	global_store_short_d16_hi v[8:9], v3, off offset:512
	v_accvgpr_read_b32 v3, a22
	v_bfe_u32 v10, v3, 16, 1
	v_add3_u32 v3, v3, v10, s80
	v_add_co_u32_e32 v10, vcc, s0, v8
	v_mfma_f32_32x32x16_bf16 a[0:15], v[106:109], v[114:117], a[0:15]
	s_nop 0
	v_addc_co_u32_e32 v11, vcc, 0, v9, vcc
	global_store_short_d16_hi v[10:11], v3, off
	v_accvgpr_read_b32 v3, a23
	v_bfe_u32 v12, v3, 16, 1
	v_add3_u32 v3, v3, v12, s80
	v_add_u32_e32 v12, 0xc00, v2
	global_store_short_d16_hi v[10:11], v3, off offset:512
	v_ashrrev_i32_e32 v13, 31, v12
	v_accvgpr_read_b32 v3, a24
	v_lshlrev_b64 v[12:13], 9, v[12:13]
	v_bfe_u32 v14, v3, 16, 1
	v_lshl_add_u64 v[12:13], v[0:1], 0, v[12:13]
	v_add3_u32 v3, v3, v14, s80
	global_store_short_d16_hi v[12:13], v3, off
	v_accvgpr_read_b32 v3, a25
	v_bfe_u32 v14, v3, 16, 1
	v_add3_u32 v3, v3, v14, s80
	global_store_short_d16_hi v[12:13], v3, off offset:512
	v_accvgpr_read_b32 v3, a26
	v_bfe_u32 v14, v3, 16, 1
	v_add3_u32 v3, v3, v14, s80
	v_add_co_u32_e32 v14, vcc, s0, v12
	v_add_u32_e32 v2, 0xe00, v2
	s_nop 0
	v_addc_co_u32_e32 v15, vcc, 0, v13, vcc
	global_store_short_d16_hi v[14:15], v3, off
	v_accvgpr_read_b32 v3, a27
	v_bfe_u32 v16, v3, 16, 1
	v_add3_u32 v3, v3, v16, s80
	global_store_short_d16_hi v[14:15], v3, off offset:512
	v_ashrrev_i32_e32 v3, 31, v2
	v_lshlrev_b64 v[2:3], 9, v[2:3]
	v_lshl_add_u64 v[0:1], v[0:1], 0, v[2:3]
	v_accvgpr_read_b32 v2, a28
	v_bfe_u32 v3, v2, 16, 1
	v_add3_u32 v2, v2, v3, s80
	global_store_short_d16_hi v[0:1], v2, off
	v_accvgpr_read_b32 v2, a29
	v_bfe_u32 v3, v2, 16, 1
	v_add3_u32 v2, v2, v3, s80
	global_store_short_d16_hi v[0:1], v2, off offset:512
	v_accvgpr_read_b32 v2, a30
	v_bfe_u32 v3, v2, 16, 1
	v_add3_u32 v16, v2, v3, s80
	v_add_co_u32_e32 v2, vcc, s0, v0
	s_nop 1
	v_addc_co_u32_e32 v3, vcc, 0, v1, vcc
	global_store_short_d16_hi v[2:3], v16, off
	v_accvgpr_read_b32 v16, a31
	v_bfe_u32 v17, v16, 16, 1
	v_add3_u32 v16, v16, v17, s80
	global_store_short_d16_hi v[2:3], v16, off offset:512
	v_accvgpr_read_b32 v16, a0
	v_bfe_u32 v17, v16, 16, 1
	v_add3_u32 v16, v16, v17, s80
	global_store_short_d16_hi v[4:5], v16, off offset:64
	v_accvgpr_read_b32 v16, a1
	v_bfe_u32 v17, v16, 16, 1
	v_add3_u32 v16, v16, v17, s80
	global_store_short_d16_hi v[4:5], v16, off offset:576
	v_accvgpr_read_b32 v4, a2
	v_bfe_u32 v5, v4, 16, 1
	v_add3_u32 v4, v4, v5, s80
	global_store_short_d16_hi v[6:7], v4, off offset:64
	v_accvgpr_read_b32 v4, a3
	v_bfe_u32 v5, v4, 16, 1
	v_add3_u32 v4, v4, v5, s80
	global_store_short_d16_hi v[6:7], v4, off offset:576
	v_accvgpr_read_b32 v4, a4
	v_bfe_u32 v5, v4, 16, 1
	v_add3_u32 v4, v4, v5, s80
	global_store_short_d16_hi v[8:9], v4, off offset:64
	v_accvgpr_read_b32 v4, a5
	v_bfe_u32 v5, v4, 16, 1
	v_add3_u32 v4, v4, v5, s80
	global_store_short_d16_hi v[8:9], v4, off offset:576
	v_accvgpr_read_b32 v4, a6
	v_bfe_u32 v5, v4, 16, 1
	v_add3_u32 v4, v4, v5, s80
	global_store_short_d16_hi v[10:11], v4, off offset:64
	v_accvgpr_read_b32 v4, a7
	v_bfe_u32 v5, v4, 16, 1
	v_add3_u32 v4, v4, v5, s80
	global_store_short_d16_hi v[10:11], v4, off offset:576
	v_accvgpr_read_b32 v4, a8
	v_bfe_u32 v5, v4, 16, 1
	v_add3_u32 v4, v4, v5, s80
	global_store_short_d16_hi v[12:13], v4, off offset:64
	v_accvgpr_read_b32 v4, a9
	v_bfe_u32 v5, v4, 16, 1
	v_add3_u32 v4, v4, v5, s80
	global_store_short_d16_hi v[12:13], v4, off offset:576
	v_accvgpr_read_b32 v4, a10
	v_bfe_u32 v5, v4, 16, 1
	v_add3_u32 v4, v4, v5, s80
	global_store_short_d16_hi v[14:15], v4, off offset:64
	v_accvgpr_read_b32 v4, a11
	v_bfe_u32 v5, v4, 16, 1
	v_add3_u32 v4, v4, v5, s80
	global_store_short_d16_hi v[14:15], v4, off offset:576
	v_accvgpr_read_b32 v4, a12
	v_bfe_u32 v5, v4, 16, 1
	v_add3_u32 v4, v4, v5, s80
	global_store_short_d16_hi v[0:1], v4, off offset:64
	v_accvgpr_read_b32 v4, a13
	v_bfe_u32 v5, v4, 16, 1
	v_add3_u32 v4, v4, v5, s80
	global_store_short_d16_hi v[0:1], v4, off offset:576
	v_accvgpr_read_b32 v0, a14
	v_bfe_u32 v1, v0, 16, 1
	v_add3_u32 v0, v0, v1, s80
	global_store_short_d16_hi v[2:3], v0, off offset:64
	v_accvgpr_read_b32 v0, a15
	v_bfe_u32 v1, v0, 16, 1
	v_add3_u32 v0, v0, v1, s80
	global_store_short_d16_hi v[2:3], v0, off offset:576
